# grid barrier spin loops: s_sleep removed (tighter polling of the arrival counter)
# speedup vs baseline: 1.0004x; 1.0004x over previous
.LBB0_14:
	global_load_dword v2, v0, s[4:5] offset:32 sc1
	s_waitcnt vmcnt(0)
	v_and_b32_e32 v2, 0xffff0000, v2
	v_cmp_ne_u32_e32 vcc, v2, v1
	s_or_b64 s[6:7], vcc, s[6:7]
	s_andn2_b64 exec, exec, s[6:7]
	s_cbranch_execnz .LBB0_14

.LBB0_46:
	global_load_dword v15, v16, s[6:7] sc1
	s_waitcnt lgkmcnt(0)
	global_load_dword v0, v16, s[8:9] sc1
	global_load_dword v1, v16, s[10:11] sc1
	global_load_dword v2, v16, s[12:13] sc1
	global_load_dword v3, v16, s[14:15] sc1
	global_load_dword v4, v16, s[30:31] sc1
	global_load_dword v5, v16, s[34:35] sc1
	global_load_dword v6, v16, s[56:57] sc1
	global_load_dword v7, v16, s[80:81] sc1
	global_load_dword v8, v16, s[82:83] sc1
	global_load_dword v9, v16, s[84:85] sc1
	global_load_dword v10, v16, s[86:87] sc1
	global_load_dword v11, v16, s[88:89] sc1
	global_load_dword v12, v16, s[90:91] sc1
	global_load_dword v13, v16, s[92:93] sc1
	global_load_dword v14, v16, s[94:95] sc1
	s_mov_b64 s[96:97], -1
	s_mov_b64 s[16:17], -1
	s_waitcnt vmcnt(14)
	v_add_u32_e32 v17, v0, v15
	s_waitcnt vmcnt(13)
	v_add_u32_e32 v17, v17, v1
	s_waitcnt vmcnt(12)
	v_add_u32_e32 v17, v17, v2
	s_waitcnt vmcnt(11)
	v_add_u32_e32 v17, v17, v3
	s_waitcnt vmcnt(10)
	v_add_u32_e32 v17, v17, v4
	s_waitcnt vmcnt(9)
	v_add_u32_e32 v17, v17, v5
	s_waitcnt vmcnt(8)
	v_add_u32_e32 v17, v17, v6
	s_waitcnt vmcnt(7)
	v_add_u32_e32 v17, v17, v7
	s_waitcnt vmcnt(6)
	v_add_u32_e32 v17, v17, v8
	s_waitcnt vmcnt(5)
	v_add_u32_e32 v17, v17, v9
	s_waitcnt vmcnt(4)
	v_add_u32_e32 v17, v17, v10
	s_waitcnt vmcnt(3)
	v_add_u32_e32 v17, v17, v11
	s_waitcnt vmcnt(2)
	v_add_u32_e32 v17, v17, v12
	s_waitcnt vmcnt(1)
	v_add_u32_e32 v17, v17, v13
	s_waitcnt vmcnt(0)
	v_add_u32_e32 v17, v17, v14
	v_cmp_eq_u32_e32 vcc, s3, v17
	s_cbranch_vccnz .LBB0_45
	s_and_b32 s18, s19, 0xff
	s_cmp_eq_u32 s18, 0
	s_mov_b64 s[28:29], -1
	s_cbranch_scc1 .LBB0_50
	s_and_b64 vcc, exec, s[28:29]
	s_cbranch_vccz .LBB0_45

.LBB0_64:
	s_and_b32 s18, s3, 0xff
	s_mov_b64 s[16:17], -1
	s_cmp_lg_u32 s18, 0
	s_mov_b64 s[34:35], -1
	s_cbranch_scc0 .LBB0_67
	s_and_b64 vcc, exec, s[34:35]
	s_cbranch_vccz .LBB0_63

.LBB0_81:
	s_and_b32 s16, s3, 0xff
	s_cmp_lg_u32 s16, 0
	s_mov_b64 s[28:29], -1
	s_cbranch_scc0 .LBB0_84
	s_mov_b64 s[34:35], -1
	s_and_b64 vcc, exec, s[28:29]
	s_cbranch_vccz .LBB0_80

.LBB0_174:
	global_load_dword v15, v16, s[6:7] sc1
	s_waitcnt lgkmcnt(0)
	global_load_dword v0, v16, s[8:9] sc1
	global_load_dword v1, v16, s[10:11] sc1
	global_load_dword v2, v16, s[12:13] sc1
	global_load_dword v3, v16, s[14:15] sc1
	global_load_dword v4, v16, s[34:35] sc1
	global_load_dword v5, v16, s[56:57] sc1
	global_load_dword v6, v16, s[80:81] sc1
	global_load_dword v7, v16, s[82:83] sc1
	global_load_dword v8, v16, s[84:85] sc1
	global_load_dword v9, v16, s[86:87] sc1
	global_load_dword v10, v16, s[88:89] sc1
	global_load_dword v11, v16, s[90:91] sc1
	global_load_dword v12, v16, s[92:93] sc1
	global_load_dword v13, v16, s[94:95] sc1
	global_load_dword v14, v16, s[96:97] sc1
	s_mov_b64 s[16:17], -1
	s_mov_b64 s[28:29], -1
	s_waitcnt vmcnt(14)
	v_add_u32_e32 v17, v0, v15
	s_waitcnt vmcnt(13)
	v_add_u32_e32 v17, v17, v1
	s_waitcnt vmcnt(12)
	v_add_u32_e32 v17, v17, v2
	s_waitcnt vmcnt(11)
	v_add_u32_e32 v17, v17, v3
	s_waitcnt vmcnt(10)
	v_add_u32_e32 v17, v17, v4
	s_waitcnt vmcnt(9)
	v_add_u32_e32 v17, v17, v5
	s_waitcnt vmcnt(8)
	v_add_u32_e32 v17, v17, v6
	s_waitcnt vmcnt(7)
	v_add_u32_e32 v17, v17, v7
	s_waitcnt vmcnt(6)
	v_add_u32_e32 v17, v17, v8
	s_waitcnt vmcnt(5)
	v_add_u32_e32 v17, v17, v9
	s_waitcnt vmcnt(4)
	v_add_u32_e32 v17, v17, v10
	s_waitcnt vmcnt(3)
	v_add_u32_e32 v17, v17, v11
	s_waitcnt vmcnt(2)
	v_add_u32_e32 v17, v17, v12
	s_waitcnt vmcnt(1)
	v_add_u32_e32 v17, v17, v13
	s_waitcnt vmcnt(0)
	v_add_u32_e32 v17, v17, v14
	v_cmp_eq_u32_e32 vcc, s3, v17
	s_cbranch_vccnz .LBB0_173
	s_and_b32 s16, s19, 0xff
	s_cmp_eq_u32 s16, 0
	s_mov_b64 s[16:17], -1
	s_mov_b64 vcc, -1
	s_cbranch_scc1 .LBB0_178
	s_and_b64 vcc, exec, vcc
	s_cbranch_vccz .LBB0_173

.LBB0_192:
	s_and_b32 s18, s3, 0xff
	s_mov_b64 s[16:17], -1
	s_cmp_lg_u32 s18, 0
	s_mov_b64 s[56:57], -1
	s_cbranch_scc0 .LBB0_195
	s_and_b64 vcc, exec, s[56:57]
	s_cbranch_vccz .LBB0_191

.LBB0_209:
	s_and_b32 s16, s3, 0xff
	s_cmp_lg_u32 s16, 0
	s_mov_b64 s[28:29], -1
	s_cbranch_scc0 .LBB0_212
	s_mov_b64 s[80:81], -1
	s_and_b64 vcc, exec, s[28:29]
	s_cbranch_vccz .LBB0_208

.LBB0_765:
	global_load_dword v15, v16, s[6:7] sc1
	s_waitcnt lgkmcnt(0)
	global_load_dword v0, v16, s[8:9] sc1
	global_load_dword v1, v16, s[10:11] sc1
	global_load_dword v2, v16, s[12:13] sc1
	global_load_dword v3, v16, s[14:15] sc1
	global_load_dword v4, v16, s[56:57] sc1
	global_load_dword v5, v16, s[58:59] sc1
	global_load_dword v6, v16, s[62:63] sc1
	global_load_dword v7, v16, s[80:81] sc1
	global_load_dword v8, v16, s[82:83] sc1
	global_load_dword v9, v16, s[86:87] sc1
	global_load_dword v10, v16, s[88:89] sc1
	global_load_dword v11, v16, s[90:91] sc1
	global_load_dword v12, v16, s[92:93] sc1
	global_load_dword v13, v16, s[94:95] sc1
	global_load_dword v14, v16, s[96:97] sc1
	s_mov_b64 s[16:17], -1
	s_mov_b64 s[28:29], -1
	s_waitcnt vmcnt(14)
	v_add_u32_e32 v17, v0, v15
	s_waitcnt vmcnt(13)
	v_add_u32_e32 v17, v17, v1
	s_waitcnt vmcnt(12)
	v_add_u32_e32 v17, v17, v2
	s_waitcnt vmcnt(11)
	v_add_u32_e32 v17, v17, v3
	s_waitcnt vmcnt(10)
	v_add_u32_e32 v17, v17, v4
	s_waitcnt vmcnt(9)
	v_add_u32_e32 v17, v17, v5
	s_waitcnt vmcnt(8)
	v_add_u32_e32 v17, v17, v6
	s_waitcnt vmcnt(7)
	v_add_u32_e32 v17, v17, v7
	s_waitcnt vmcnt(6)
	v_add_u32_e32 v17, v17, v8
	s_waitcnt vmcnt(5)
	v_add_u32_e32 v17, v17, v9
	s_waitcnt vmcnt(4)
	v_add_u32_e32 v17, v17, v10
	s_waitcnt vmcnt(3)
	v_add_u32_e32 v17, v17, v11
	s_waitcnt vmcnt(2)
	v_add_u32_e32 v17, v17, v12
	s_waitcnt vmcnt(1)
	v_add_u32_e32 v17, v17, v13
	s_waitcnt vmcnt(0)
	v_add_u32_e32 v17, v17, v14
	v_cmp_eq_u32_e32 vcc, s3, v17
	s_cbranch_vccnz .LBB0_764
	s_and_b32 s16, s19, 0xff
	s_cmp_eq_u32 s16, 0
	s_mov_b64 s[16:17], -1
	s_mov_b64 vcc, -1
	s_cbranch_scc1 .LBB0_769
	s_and_b64 vcc, exec, vcc
	s_cbranch_vccz .LBB0_764

.LBB0_783:
	s_and_b32 s18, s3, 0xff
	s_mov_b64 s[16:17], -1
	s_cmp_lg_u32 s18, 0
	s_mov_b64 s[58:59], -1
	s_cbranch_scc0 .LBB0_786
	s_and_b64 vcc, exec, s[58:59]
	s_cbranch_vccz .LBB0_782

.LBB0_800:
	s_and_b32 s16, s3, 0xff
	s_cmp_lg_u32 s16, 0
	s_mov_b64 s[28:29], -1
	s_cbranch_scc0 .LBB0_803
	s_mov_b64 s[62:63], -1
	s_and_b64 vcc, exec, s[28:29]
	s_cbranch_vccz .LBB0_799

.LBB0_940:
	global_load_dword v15, v16, s[10:11] sc1
	s_waitcnt lgkmcnt(0)
	global_load_dword v0, v16, s[12:13] sc1
	global_load_dword v1, v16, s[40:41] sc1
	global_load_dword v2, v16, s[42:43] sc1
	global_load_dword v3, v16, s[46:47] sc1
	global_load_dword v4, v16, s[48:49] sc1
	global_load_dword v5, v16, s[52:53] sc1
	global_load_dword v6, v16, s[56:57] sc1
	global_load_dword v7, v16, s[62:63] sc1
	global_load_dword v8, v16, s[66:67] sc1
	global_load_dword v9, v16, s[68:69] sc1
	global_load_dword v10, v16, s[74:75] sc1
	global_load_dword v11, v16, s[80:81] sc1
	global_load_dword v12, v16, s[82:83] sc1
	global_load_dword v13, v16, s[84:85] sc1
	global_load_dword v14, v16, s[86:87] sc1
	s_mov_b64 s[16:17], -1
	s_mov_b64 s[28:29], -1
	s_waitcnt vmcnt(14)
	v_add_u32_e32 v17, v0, v15
	s_waitcnt vmcnt(13)
	v_add_u32_e32 v17, v17, v1
	s_waitcnt vmcnt(12)
	v_add_u32_e32 v17, v17, v2
	s_waitcnt vmcnt(11)
	v_add_u32_e32 v17, v17, v3
	s_waitcnt vmcnt(10)
	v_add_u32_e32 v17, v17, v4
	s_waitcnt vmcnt(9)
	v_add_u32_e32 v17, v17, v5
	s_waitcnt vmcnt(8)
	v_add_u32_e32 v17, v17, v6
	s_waitcnt vmcnt(7)
	v_add_u32_e32 v17, v17, v7
	s_waitcnt vmcnt(6)
	v_add_u32_e32 v17, v17, v8
	s_waitcnt vmcnt(5)
	v_add_u32_e32 v17, v17, v9
	s_waitcnt vmcnt(4)
	v_add_u32_e32 v17, v17, v10
	s_waitcnt vmcnt(3)
	v_add_u32_e32 v17, v17, v11
	s_waitcnt vmcnt(2)
	v_add_u32_e32 v17, v17, v12
	s_waitcnt vmcnt(1)
	v_add_u32_e32 v17, v17, v13
	s_waitcnt vmcnt(0)
	v_add_u32_e32 v17, v17, v14
	v_cmp_eq_u32_e32 vcc, s3, v17
	s_cbranch_vccnz .LBB0_939
	s_and_b32 s16, s19, 0xff
	s_cmp_eq_u32 s16, 0
	s_mov_b64 s[16:17], -1
	s_mov_b64 s[88:89], -1
	s_cbranch_scc1 .LBB0_944
	s_and_b64 vcc, exec, s[88:89]
	s_cbranch_vccz .LBB0_938

.LBB0_958:
	s_and_b32 s18, s3, 0xff
	s_mov_b64 s[16:17], -1
	s_cmp_lg_u32 s18, 0
	s_mov_b64 s[52:53], -1
	s_cbranch_scc0 .LBB0_961
	s_and_b64 vcc, exec, s[52:53]
	s_cbranch_vccz .LBB0_957

.LBB0_975:
	s_and_b32 s16, s3, 0xff
	s_cmp_lg_u32 s16, 0
	s_mov_b64 s[28:29], -1
	s_cbranch_scc0 .LBB0_978
	s_mov_b64 s[56:57], -1
	s_and_b64 vcc, exec, s[28:29]
	s_cbranch_vccz .LBB0_974

.LBB0_1010:
	global_load_dword v15, v16, s[10:11] sc1
	s_waitcnt lgkmcnt(0)
	global_load_dword v0, v16, s[12:13] sc1
	global_load_dword v1, v16, s[40:41] sc1
	global_load_dword v2, v16, s[42:43] sc1
	global_load_dword v3, v16, s[46:47] sc1
	global_load_dword v4, v16, s[48:49] sc1
	global_load_dword v5, v16, s[52:53] sc1
	global_load_dword v6, v16, s[56:57] sc1
	global_load_dword v7, v16, s[62:63] sc1
	global_load_dword v8, v16, s[64:65] sc1
	global_load_dword v9, v16, s[66:67] sc1
	global_load_dword v10, v16, s[68:69] sc1
	global_load_dword v11, v16, s[74:75] sc1
	global_load_dword v12, v16, s[80:81] sc1
	global_load_dword v13, v16, s[82:83] sc1
	global_load_dword v14, v16, s[84:85] sc1
	s_mov_b64 s[16:17], -1
	s_mov_b64 s[28:29], -1
	s_waitcnt vmcnt(14)
	v_add_u32_e32 v17, v0, v15
	s_waitcnt vmcnt(13)
	v_add_u32_e32 v17, v17, v1
	s_waitcnt vmcnt(12)
	v_add_u32_e32 v17, v17, v2
	s_waitcnt vmcnt(11)
	v_add_u32_e32 v17, v17, v3
	s_waitcnt vmcnt(10)
	v_add_u32_e32 v17, v17, v4
	s_waitcnt vmcnt(9)
	v_add_u32_e32 v17, v17, v5
	s_waitcnt vmcnt(8)
	v_add_u32_e32 v17, v17, v6
	s_waitcnt vmcnt(7)
	v_add_u32_e32 v17, v17, v7
	s_waitcnt vmcnt(6)
	v_add_u32_e32 v17, v17, v8
	s_waitcnt vmcnt(5)
	v_add_u32_e32 v17, v17, v9
	s_waitcnt vmcnt(4)
	v_add_u32_e32 v17, v17, v10
	s_waitcnt vmcnt(3)
	v_add_u32_e32 v17, v17, v11
	s_waitcnt vmcnt(2)
	v_add_u32_e32 v17, v17, v12
	s_waitcnt vmcnt(1)
	v_add_u32_e32 v17, v17, v13
	s_waitcnt vmcnt(0)
	v_add_u32_e32 v17, v17, v14
	v_cmp_eq_u32_e32 vcc, s3, v17
	s_cbranch_vccnz .LBB0_1009
	s_and_b32 s16, s19, 0xff
	s_cmp_eq_u32 s16, 0
	s_mov_b64 s[16:17], -1
	s_mov_b64 s[86:87], -1
	s_cbranch_scc1 .LBB0_1014
	s_and_b64 vcc, exec, s[86:87]
	s_cbranch_vccz .LBB0_1009

.LBB0_1076:
	global_load_dword v15, v16, s[6:7] sc1
	s_waitcnt lgkmcnt(0)
	global_load_dword v0, v16, s[40:41] sc1
	global_load_dword v1, v16, s[42:43] sc1
	global_load_dword v2, v16, s[46:47] sc1
	global_load_dword v3, v16, s[48:49] sc1
	global_load_dword v4, v16, s[52:53] sc1
	global_load_dword v5, v16, s[56:57] sc1
	global_load_dword v6, v16, s[62:63] sc1
	global_load_dword v7, v16, s[64:65] sc1
	global_load_dword v8, v16, s[66:67] sc1
	global_load_dword v9, v16, s[68:69] sc1
	global_load_dword v10, v16, s[74:75] sc1
	global_load_dword v11, v16, s[80:81] sc1
	global_load_dword v12, v16, s[82:83] sc1
	global_load_dword v13, v16, s[84:85] sc1
	global_load_dword v14, v16, s[86:87] sc1
	s_mov_b64 s[16:17], -1
	s_mov_b64 s[28:29], -1
	s_waitcnt vmcnt(14)
	v_add_u32_e32 v17, v0, v15
	s_waitcnt vmcnt(13)
	v_add_u32_e32 v17, v17, v1
	s_waitcnt vmcnt(12)
	v_add_u32_e32 v17, v17, v2
	s_waitcnt vmcnt(11)
	v_add_u32_e32 v17, v17, v3
	s_waitcnt vmcnt(10)
	v_add_u32_e32 v17, v17, v4
	s_waitcnt vmcnt(9)
	v_add_u32_e32 v17, v17, v5
	s_waitcnt vmcnt(8)
	v_add_u32_e32 v17, v17, v6
	s_waitcnt vmcnt(7)
	v_add_u32_e32 v17, v17, v7
	s_waitcnt vmcnt(6)
	v_add_u32_e32 v17, v17, v8
	s_waitcnt vmcnt(5)
	v_add_u32_e32 v17, v17, v9
	s_waitcnt vmcnt(4)
	v_add_u32_e32 v17, v17, v10
	s_waitcnt vmcnt(3)
	v_add_u32_e32 v17, v17, v11
	s_waitcnt vmcnt(2)
	v_add_u32_e32 v17, v17, v12
	s_waitcnt vmcnt(1)
	v_add_u32_e32 v17, v17, v13
	s_waitcnt vmcnt(0)
	v_add_u32_e32 v17, v17, v14
	v_cmp_eq_u32_e32 vcc, s3, v17
	s_cbranch_vccnz .LBB0_1075
	s_and_b32 s16, s19, 0xff
	s_cmp_eq_u32 s16, 0
	s_mov_b64 s[16:17], -1
	s_mov_b64 s[88:89], -1
	s_cbranch_scc1 .LBB0_1080
	s_and_b64 vcc, exec, s[88:89]
	s_cbranch_vccz .LBB0_1074

.LBB0_1206:
	global_load_dword v15, v16, s[6:7] sc1
	s_waitcnt lgkmcnt(0)
	global_load_dword v0, v16, s[36:37] sc1
	global_load_dword v1, v16, s[38:39] sc1
	global_load_dword v2, v16, s[40:41] sc1
	global_load_dword v3, v16, s[42:43] sc1
	global_load_dword v4, v16, s[46:47] sc1
	global_load_dword v5, v16, s[48:49] sc1
	global_load_dword v6, v16, s[50:51] sc1
	global_load_dword v7, v16, s[52:53] sc1
	global_load_dword v8, v16, s[54:55] sc1
	global_load_dword v9, v16, s[56:57] sc1
	global_load_dword v10, v16, s[62:63] sc1
	global_load_dword v11, v16, s[64:65] sc1
	global_load_dword v12, v16, s[66:67] sc1
	global_load_dword v13, v16, s[68:69] sc1
	global_load_dword v14, v16, s[74:75] sc1
	s_mov_b64 s[16:17], -1
	s_mov_b64 s[28:29], -1
	s_waitcnt vmcnt(14)
	v_add_u32_e32 v17, v0, v15
	s_waitcnt vmcnt(13)
	v_add_u32_e32 v17, v17, v1
	s_waitcnt vmcnt(12)
	v_add_u32_e32 v17, v17, v2
	s_waitcnt vmcnt(11)
	v_add_u32_e32 v17, v17, v3
	s_waitcnt vmcnt(10)
	v_add_u32_e32 v17, v17, v4
	s_waitcnt vmcnt(9)
	v_add_u32_e32 v17, v17, v5
	s_waitcnt vmcnt(8)
	v_add_u32_e32 v17, v17, v6
	s_waitcnt vmcnt(7)
	v_add_u32_e32 v17, v17, v7
	s_waitcnt vmcnt(6)
	v_add_u32_e32 v17, v17, v8
	s_waitcnt vmcnt(5)
	v_add_u32_e32 v17, v17, v9
	s_waitcnt vmcnt(4)
	v_add_u32_e32 v17, v17, v10
	s_waitcnt vmcnt(3)
	v_add_u32_e32 v17, v17, v11
	s_waitcnt vmcnt(2)
	v_add_u32_e32 v17, v17, v12
	s_waitcnt vmcnt(1)
	v_add_u32_e32 v17, v17, v13
	s_waitcnt vmcnt(0)
	v_add_u32_e32 v17, v17, v14
	v_cmp_eq_u32_e32 vcc, s3, v17
	s_cbranch_vccnz .LBB0_1205
	s_and_b32 s16, s19, 0xff
	s_cmp_eq_u32 s16, 0
	s_mov_b64 s[16:17], -1
	s_mov_b64 s[78:79], -1
	s_cbranch_scc1 .LBB0_1210
	s_and_b64 vcc, exec, s[78:79]
	s_cbranch_vccz .LBB0_1204

.LBB0_1224:
	s_and_b32 s18, s3, 0xff
	s_mov_b64 s[16:17], -1
	s_cmp_lg_u32 s18, 0
	s_mov_b64 s[48:49], -1
	s_cbranch_scc0 .LBB0_1227
	s_and_b64 vcc, exec, s[48:49]
	s_cbranch_vccz .LBB0_1223

.LBB0_1241:
	s_and_b32 s16, s3, 0xff
	s_cmp_lg_u32 s16, 0
	s_mov_b64 s[28:29], -1
	s_cbranch_scc0 .LBB0_1244
	s_mov_b64 s[48:49], -1
	s_and_b64 vcc, exec, s[28:29]
	s_cbranch_vccz .LBB0_1240

.LBB0_1304:
	global_load_dword v15, v16, s[6:7] sc1
	s_waitcnt lgkmcnt(0)
	global_load_dword v0, v16, s[14:15] sc1
	global_load_dword v1, v16, s[36:37] sc1
	global_load_dword v2, v16, s[38:39] sc1
	global_load_dword v3, v16, s[40:41] sc1
	global_load_dword v4, v16, s[42:43] sc1
	global_load_dword v5, v16, s[46:47] sc1
	global_load_dword v6, v16, s[48:49] sc1
	global_load_dword v7, v16, s[50:51] sc1
	global_load_dword v8, v16, s[52:53] sc1
	global_load_dword v9, v16, s[54:55] sc1
	global_load_dword v10, v16, s[56:57] sc1
	global_load_dword v11, v16, s[62:63] sc1
	global_load_dword v12, v16, s[64:65] sc1
	global_load_dword v13, v16, s[66:67] sc1
	global_load_dword v14, v16, s[68:69] sc1
	s_mov_b64 s[16:17], -1
	s_mov_b64 s[28:29], -1
	s_waitcnt vmcnt(14)
	v_add_u32_e32 v17, v0, v15
	s_waitcnt vmcnt(13)
	v_add_u32_e32 v17, v17, v1
	s_waitcnt vmcnt(12)
	v_add_u32_e32 v17, v17, v2
	s_waitcnt vmcnt(11)
	v_add_u32_e32 v17, v17, v3
	s_waitcnt vmcnt(10)
	v_add_u32_e32 v17, v17, v4
	s_waitcnt vmcnt(9)
	v_add_u32_e32 v17, v17, v5
	s_waitcnt vmcnt(8)
	v_add_u32_e32 v17, v17, v6
	s_waitcnt vmcnt(7)
	v_add_u32_e32 v17, v17, v7
	s_waitcnt vmcnt(6)
	v_add_u32_e32 v17, v17, v8
	s_waitcnt vmcnt(5)
	v_add_u32_e32 v17, v17, v9
	s_waitcnt vmcnt(4)
	v_add_u32_e32 v17, v17, v10
	s_waitcnt vmcnt(3)
	v_add_u32_e32 v17, v17, v11
	s_waitcnt vmcnt(2)
	v_add_u32_e32 v17, v17, v12
	s_waitcnt vmcnt(1)
	v_add_u32_e32 v17, v17, v13
	s_waitcnt vmcnt(0)
	v_add_u32_e32 v17, v17, v14
	v_cmp_eq_u32_e32 vcc, s3, v17
	s_cbranch_vccnz .LBB0_1303
	s_and_b32 s16, s19, 0xff
	s_cmp_eq_u32 s16, 0
	s_mov_b64 s[16:17], -1
	s_mov_b64 s[74:75], -1
	s_cbranch_scc1 .LBB0_1308
	s_and_b64 vcc, exec, s[74:75]
	s_cbranch_vccz .LBB0_1303

.LBB0_1322:
	s_and_b32 s18, s3, 0xff
	s_mov_b64 s[16:17], -1
	s_cmp_lg_u32 s18, 0
	s_mov_b64 s[46:47], -1
	s_cbranch_scc0 .LBB0_1325
	s_and_b64 vcc, exec, s[46:47]
	s_cbranch_vccz .LBB0_1321

.LBB0_1377:
	global_load_dword v15, v16, s[6:7] sc1
	s_waitcnt lgkmcnt(0)
	global_load_dword v0, v16, s[14:15] sc1
	global_load_dword v1, v16, s[36:37] sc1
	global_load_dword v2, v16, s[38:39] sc1
	global_load_dword v3, v16, s[40:41] sc1
	global_load_dword v4, v16, s[42:43] sc1
	global_load_dword v5, v16, s[44:45] sc1
	global_load_dword v6, v16, s[46:47] sc1
	global_load_dword v7, v16, s[48:49] sc1
	global_load_dword v8, v16, s[50:51] sc1
	global_load_dword v9, v16, s[52:53] sc1
	global_load_dword v10, v16, s[54:55] sc1
	global_load_dword v11, v16, s[56:57] sc1
	global_load_dword v12, v16, s[58:59] sc1
	global_load_dword v13, v16, s[62:63] sc1
	global_load_dword v14, v16, s[64:65] sc1
	s_mov_b64 s[16:17], -1
	s_mov_b64 s[28:29], -1
	s_waitcnt vmcnt(14)
	v_add_u32_e32 v17, v0, v15
	s_waitcnt vmcnt(13)
	v_add_u32_e32 v17, v17, v1
	s_waitcnt vmcnt(12)
	v_add_u32_e32 v17, v17, v2
	s_waitcnt vmcnt(11)
	v_add_u32_e32 v17, v17, v3
	s_waitcnt vmcnt(10)
	v_add_u32_e32 v17, v17, v4
	s_waitcnt vmcnt(9)
	v_add_u32_e32 v17, v17, v5
	s_waitcnt vmcnt(8)
	v_add_u32_e32 v17, v17, v6
	s_waitcnt vmcnt(7)
	v_add_u32_e32 v17, v17, v7
	s_waitcnt vmcnt(6)
	v_add_u32_e32 v17, v17, v8
	s_waitcnt vmcnt(5)
	v_add_u32_e32 v17, v17, v9
	s_waitcnt vmcnt(4)
	v_add_u32_e32 v17, v17, v10
	s_waitcnt vmcnt(3)
	v_add_u32_e32 v17, v17, v11
	s_waitcnt vmcnt(2)
	v_add_u32_e32 v17, v17, v12
	s_waitcnt vmcnt(1)
	v_add_u32_e32 v17, v17, v13
	s_waitcnt vmcnt(0)
	v_add_u32_e32 v17, v17, v14
	v_cmp_eq_u32_e32 vcc, s3, v17
	s_cbranch_vccnz .LBB0_1376
	s_and_b32 s16, s19, 0xff
	s_cmp_eq_u32 s16, 0
	s_mov_b64 s[16:17], -1
	s_mov_b64 s[66:67], -1
	s_cbranch_scc1 .LBB0_1381
	s_and_b64 vcc, exec, s[66:67]
	s_cbranch_vccz .LBB0_1376

.LBB0_1395:
	s_and_b32 s18, s3, 0xff
	s_mov_b64 s[16:17], -1
	s_cmp_lg_u32 s18, 0
	s_mov_b64 s[44:45], -1
	s_cbranch_scc0 .LBB0_1398
	s_and_b64 vcc, exec, s[44:45]
	s_cbranch_vccz .LBB0_1394

.LBB0_1412:
	s_and_b32 s16, s3, 0xff
	s_cmp_lg_u32 s16, 0
	s_mov_b64 s[28:29], -1
	s_cbranch_scc0 .LBB0_1415
	s_mov_b64 s[46:47], -1
	s_and_b64 vcc, exec, s[28:29]
	s_cbranch_vccz .LBB0_1411

.LBB0_1443:
	global_load_dword v15, v16, s[6:7] sc1
	s_waitcnt lgkmcnt(0)
	global_load_dword v0, v16, s[14:15] sc1
	global_load_dword v1, v16, s[36:37] sc1
	global_load_dword v2, v16, s[38:39] sc1
	global_load_dword v3, v16, s[40:41] sc1
	global_load_dword v4, v16, s[42:43] sc1
	global_load_dword v5, v16, s[44:45] sc1
	global_load_dword v6, v16, s[46:47] sc1
	global_load_dword v7, v16, s[48:49] sc1
	global_load_dword v8, v16, s[50:51] sc1
	global_load_dword v9, v16, s[52:53] sc1
	global_load_dword v10, v16, s[54:55] sc1
	global_load_dword v11, v16, s[56:57] sc1
	global_load_dword v12, v16, s[58:59] sc1
	global_load_dword v13, v16, s[60:61] sc1
	global_load_dword v14, v16, s[62:63] sc1
	s_mov_b64 s[16:17], -1
	s_mov_b64 s[28:29], -1
	s_waitcnt vmcnt(14)
	v_add_u32_e32 v17, v0, v15
	s_waitcnt vmcnt(13)
	v_add_u32_e32 v17, v17, v1
	s_waitcnt vmcnt(12)
	v_add_u32_e32 v17, v17, v2
	s_waitcnt vmcnt(11)
	v_add_u32_e32 v17, v17, v3
	s_waitcnt vmcnt(10)
	v_add_u32_e32 v17, v17, v4
	s_waitcnt vmcnt(9)
	v_add_u32_e32 v17, v17, v5
	s_waitcnt vmcnt(8)
	v_add_u32_e32 v17, v17, v6
	s_waitcnt vmcnt(7)
	v_add_u32_e32 v17, v17, v7
	s_waitcnt vmcnt(6)
	v_add_u32_e32 v17, v17, v8
	s_waitcnt vmcnt(5)
	v_add_u32_e32 v17, v17, v9
	s_waitcnt vmcnt(4)
	v_add_u32_e32 v17, v17, v10
	s_waitcnt vmcnt(3)
	v_add_u32_e32 v17, v17, v11
	s_waitcnt vmcnt(2)
	v_add_u32_e32 v17, v17, v12
	s_waitcnt vmcnt(1)
	v_add_u32_e32 v17, v17, v13
	s_waitcnt vmcnt(0)
	v_add_u32_e32 v17, v17, v14
	v_cmp_eq_u32_e32 vcc, s3, v17
	s_cbranch_vccnz .LBB0_1442
	s_and_b32 s16, s19, 0xff
	s_cmp_eq_u32 s16, 0
	s_mov_b64 s[16:17], -1
	s_mov_b64 s[64:65], -1
	s_cbranch_scc1 .LBB0_1447
	s_and_b64 vcc, exec, s[64:65]
	s_cbranch_vccz .LBB0_1442

.LBB0_1508:
	global_load_dword v15, v16, s[6:7] sc1
	s_waitcnt lgkmcnt(0)
	global_load_dword v0, v16, s[8:9] sc1
	global_load_dword v1, v16, s[12:13] sc1
	global_load_dword v2, v16, s[14:15] sc1
	global_load_dword v3, v16, s[16:17] sc1
	global_load_dword v4, v16, s[30:31] sc1
	global_load_dword v5, v16, s[36:37] sc1
	global_load_dword v6, v16, s[38:39] sc1
	global_load_dword v7, v16, s[40:41] sc1
	global_load_dword v8, v16, s[42:43] sc1
	global_load_dword v9, v16, s[44:45] sc1
	global_load_dword v10, v16, s[46:47] sc1
	global_load_dword v11, v16, s[48:49] sc1
	global_load_dword v12, v16, s[50:51] sc1
	global_load_dword v13, v16, s[52:53] sc1
	global_load_dword v14, v16, s[54:55] sc1
	s_mov_b64 s[56:57], -1
	s_mov_b64 s[28:29], -1
	s_waitcnt vmcnt(14)
	v_add_u32_e32 v17, v0, v15
	s_waitcnt vmcnt(13)
	v_add_u32_e32 v17, v17, v1
	s_waitcnt vmcnt(12)
	v_add_u32_e32 v17, v17, v2
	s_waitcnt vmcnt(11)
	v_add_u32_e32 v17, v17, v3
	s_waitcnt vmcnt(10)
	v_add_u32_e32 v17, v17, v4
	s_waitcnt vmcnt(9)
	v_add_u32_e32 v17, v17, v5
	s_waitcnt vmcnt(8)
	v_add_u32_e32 v17, v17, v6
	s_waitcnt vmcnt(7)
	v_add_u32_e32 v17, v17, v7
	s_waitcnt vmcnt(6)
	v_add_u32_e32 v17, v17, v8
	s_waitcnt vmcnt(5)
	v_add_u32_e32 v17, v17, v9
	s_waitcnt vmcnt(4)
	v_add_u32_e32 v17, v17, v10
	s_waitcnt vmcnt(3)
	v_add_u32_e32 v17, v17, v11
	s_waitcnt vmcnt(2)
	v_add_u32_e32 v17, v17, v12
	s_waitcnt vmcnt(1)
	v_add_u32_e32 v17, v17, v13
	s_waitcnt vmcnt(0)
	v_add_u32_e32 v17, v17, v14
	v_cmp_eq_u32_e32 vcc, s19, v17
	s_cbranch_vccnz .LBB0_1507
	s_and_b32 s18, s27, 0xff
	s_cmp_eq_u32 s18, 0
	s_mov_b64 s[58:59], -1
	s_cbranch_scc1 .LBB0_1512
	s_and_b64 vcc, exec, s[58:59]
	s_cbranch_vccz .LBB0_1507

.LBB0_1526:
	s_and_b32 s18, s19, 0xff
	s_mov_b64 s[30:31], -1
	s_cmp_lg_u32 s18, 0
	s_mov_b64 s[38:39], -1
	s_cbranch_scc0 .LBB0_1529
	s_and_b64 vcc, exec, s[38:39]
	s_cbranch_vccz .LBB0_1525

.LBB0_1543:
	s_and_b32 s18, s19, 0xff
	s_cmp_lg_u32 s18, 0
	s_mov_b64 s[36:37], -1
	s_cbranch_scc0 .LBB0_1546
	s_mov_b64 s[38:39], -1
	s_and_b64 vcc, exec, s[36:37]
	s_cbranch_vccz .LBB0_1542
